# group-A half releases issued right after each half's last fragment read (counted LDS waits behind them bumped by one)
# speedup vs baseline: 1.0062x; 1.0062x over previous
; #define LAS __attribute__((address_space(3)))
; __device__ __forceinline__ f32x16 mma32(bf16x8 a, bf16x8 b, f32x16 c) { return __builtin_amdgcn_mfma_f32_32x32x16_bf16(a, b, c, 0, 0, 0); }
; __device__ __forceinline__ void delta_scan_task(const P& p, int l, int s, int h, int sl, LAS unsigned char* ldsw, int lane) {
;     ...
;         for (int ti = 0; ti < 2; ++ti) {
; #pragma unroll
;             for (int g = 0; g < 4; ++g) { const f32x4v ub4 = FRAGF4(bufA, 32 + ti * 4 + g, lane); u[ti][4 * g] = ub4.x; u[ti][4 * g + 1] = ub4.y; u[ti][4 * g + 2] = ub4.z; u[ti][4 * g + 3] = ub4.w; }
;             o[ti] = zero16();
; #pragma unroll
;             for (int ks = 0; ks < 8; ++ks) {
;                 const bf16x8 b = *(const LAS bf16x8*)(ST + r * 136 + 16 * ks + 8 * hh);
;                 u[ti] = mma32(FRAG16(bufA, ti * 8 + ks, lane), b, u[ti]); o[ti] = mma32(FRAG16(bufA, 16 + ti * 8 + ks, lane), b, o[ti]);
;             }
;         }
.LBB0_1491:
.LBB0_1502:
	s_waitcnt lgkmcnt(0)
	v_add_u32_e32 v172, v194, v148
	s_add_i32 s34, s7, 1
	ds_read_b128 v[98:101], v209 offset:49152
	ds_read_b128 v[102:105], v209 offset:50176
	ds_read_b128 v[106:109], v209 offset:51200
	ds_read_b128 v[110:113], v209 offset:52224
	ds_read_b128 v[70:73], v172
	ds_read_b128 v[236:239], v209 offset:16384
	ds_read_b128 v[240:243], v209 offset:32768
	ds_read_b128 v[130:133], v172 offset:32
	ds_read_b128 v[244:247], v209 offset:17408
	ds_read_b128 v[168:171], v209 offset:33792
	ds_read_b128 v[212:215], v172 offset:64
	ds_read_b128 v[232:235], v209 offset:18432
	s_waitcnt lgkmcnt(6)
	v_mfma_f32_32x32x16_bf16 v[98:113], v[236:239], v[70:73], v[98:113]
	ds_read_b128 v[66:69], v209 offset:34816
	s_waitcnt lgkmcnt(6)
	v_mfma_f32_32x32x16_bf16 v[82:97], v[240:243], v[70:73], 0
	ds_read_b128 v[134:137], v172 offset:96
	ds_read_b128 v[236:239], v209 offset:19456
	s_waitcnt lgkmcnt(6)
	v_mfma_f32_32x32x16_bf16 v[98:113], v[244:247], v[130:133], v[98:113]
	ds_read_b128 v[240:243], v209 offset:35840
	s_waitcnt lgkmcnt(6)
	v_mfma_f32_32x32x16_bf16 v[82:97], v[168:171], v[130:133], v[82:97]
	ds_read_b128 v[216:219], v172 offset:128
	ds_read_b128 v[244:247], v209 offset:20480
	s_waitcnt lgkmcnt(6)
	v_mfma_f32_32x32x16_bf16 v[98:113], v[232:235], v[212:215], v[98:113]
	ds_read_b128 v[168:171], v209 offset:36864
	s_waitcnt lgkmcnt(6)
	v_mfma_f32_32x32x16_bf16 v[82:97], v[66:69], v[212:215], v[82:97]
	ds_read_b128 v[220:223], v172 offset:160
	ds_read_b128 v[232:235], v209 offset:21504
	s_waitcnt lgkmcnt(6)
	v_mfma_f32_32x32x16_bf16 v[98:113], v[236:239], v[134:137], v[98:113]
	ds_read_b128 v[66:69], v209 offset:37888
	s_waitcnt lgkmcnt(6)
	v_mfma_f32_32x32x16_bf16 v[82:97], v[240:243], v[134:137], v[82:97]
	ds_read_b128 v[224:227], v172 offset:192
	ds_read_b128 v[236:239], v209 offset:22528
	s_waitcnt lgkmcnt(6)
	v_mfma_f32_32x32x16_bf16 v[98:113], v[244:247], v[216:219], v[98:113]
	ds_read_b128 v[240:243], v209 offset:38912
	s_waitcnt lgkmcnt(6)
	v_mfma_f32_32x32x16_bf16 v[82:97], v[168:171], v[216:219], v[82:97]
	ds_read_b128 v[228:231], v172 offset:224
	ds_read_b128 v[244:247], v209 offset:23552
	s_waitcnt lgkmcnt(6)
	v_mfma_f32_32x32x16_bf16 v[98:113], v[232:235], v[220:223], v[98:113]
	ds_read_b128 v[168:171], v209 offset:39936
	s_and_saveexec_b64 s[100:101], s[0:1]
	v_mov_b32_e32 v255, s34
	ds_write_b32 v163, v255 offset:13336
	s_or_b64 exec, exec, s[100:101]
	s_waitcnt lgkmcnt(7)
	v_mfma_f32_32x32x16_bf16 v[82:97], v[66:69], v[220:223], v[82:97]
	s_waitcnt lgkmcnt(5)
	v_mfma_f32_32x32x16_bf16 v[98:113], v[236:239], v[224:227], v[98:113]
	s_waitcnt lgkmcnt(4)
	v_mfma_f32_32x32x16_bf16 v[82:97], v[240:243], v[224:227], v[82:97]
	s_waitcnt lgkmcnt(2)
	v_mfma_f32_32x32x16_bf16 v[98:113], v[244:247], v[228:231], v[98:113]
	s_waitcnt lgkmcnt(1)
	v_mfma_f32_32x32x16_bf16 v[82:97], v[168:171], v[228:231], v[82:97]
	s_waitcnt lgkmcnt(0)
	ds_read_b32 v66, v163 offset:13316
	s_waitcnt lgkmcnt(0)
	v_cmp_lt_u32_e32 vcc, s7, v66
	s_cbranch_vccnz .Ldp1_done
	s_mov_b32 s4, 1
	s_branch .Ldp1_1494

; __device__ __forceinline__ unsigned pk2(float lo, float hi) { f32x2_t v = {lo, hi}; bf16x2_t b = __builtin_convertvector(v, bf16x2_t); return __builtin_bit_cast(unsigned, b); }
; #define LAS __attribute__((address_space(3)))
; __device__ __forceinline__ f32x16 mma32(bf16x8 a, bf16x8 b, f32x16 c) { return __builtin_amdgcn_mfma_f32_32x32x16_bf16(a, b, c, 0, 0, 0); }
; #define LDS_WAIT() asm volatile("s_waitcnt lgkmcnt(0)" ::: "memory")
; __device__ __forceinline__ void delta_scan_task(const P& p, int l, int s, int h, int sl, LAS unsigned char* ldsw, int lane) {
;     ...
;         for (int ti = 0; ti < 2; ++ti) {
; #pragma unroll
;             for (int g = 0; g < 4; ++g) { const f32x4v ub4 = FRAGF4(bufA, 32 + ti * 4 + g, lane); u[ti][4 * g] = ub4.x; u[ti][4 * g + 1] = ub4.y; u[ti][4 * g + 2] = ub4.z; u[ti][4 * g + 3] = ub4.w; }
;             o[ti] = zero16();
; #pragma unroll
;             for (int ks = 0; ks < 8; ++ks) {
;                 const bf16x8 b = *(const LAS bf16x8*)(ST + r * 136 + 16 * ks + 8 * hh);
;                 u[ti] = mma32(FRAG16(bufA, ti * 8 + ks, lane), b, u[ti]); o[ti] = mma32(FRAG16(bufA, 16 + ti * 8 + ks, lane), b, o[ti]);
;             }
;         }
; #pragma unroll
;         for (int ti = 0; ti < 2; ++ti)
; #pragma unroll
;             for (int g = 0; g < 4; ++g) { u32x2v w; w.x = pk2(u[ti][4 * g], u[ti][4 * g + 1]); w.y = pk2(u[ti][4 * g + 2], u[ti][4 * g + 3]); *(LAS u32x2v*)(UT + r * 72 + 32 * ti + 8 * g + 4 * hh) = w; }
;         LDS_WAIT();
;         if (SCAN_LOADERS) { if (lane == 0) FL[3] = (unsigned)n + 1u; lds_wait_ge(FL + 2, (unsigned)n + 1u, FL + 5); }
.Ldp1_done:
	s_waitcnt lgkmcnt(0)
	ds_read_b128 v[114:117], v209 offset:53248
	ds_read_b128 v[118:121], v209 offset:54272
	ds_read_b128 v[122:125], v209 offset:55296
	ds_read_b128 v[126:129], v209 offset:56320
	ds_read_b128 v[236:239], v209 offset:24576
	ds_read_b128 v[240:243], v209 offset:40960
	ds_read_b128 v[244:247], v209 offset:25600
	ds_read_b128 v[168:171], v209 offset:41984
	ds_read_b128 v[232:235], v209 offset:26624
	s_waitcnt lgkmcnt(4)
	v_mfma_f32_32x32x16_bf16 v[114:129], v[236:239], v[70:73], v[114:129]
	ds_read_b128 v[236:239], v209 offset:43008
	s_waitcnt lgkmcnt(4)
	v_mfma_f32_32x32x16_bf16 v[66:81], v[240:243], v[70:73], 0
	ds_read_b128 v[240:243], v209 offset:27648
	s_waitcnt lgkmcnt(4)
	v_mfma_f32_32x32x16_bf16 v[114:129], v[244:247], v[130:133], v[114:129]
	ds_read_b128 v[244:247], v209 offset:44032
	s_waitcnt lgkmcnt(4)
	v_mfma_f32_32x32x16_bf16 v[66:81], v[168:171], v[130:133], v[66:81]
	ds_read_b128 v[168:171], v209 offset:28672
	s_waitcnt lgkmcnt(4)
	v_mfma_f32_32x32x16_bf16 v[114:129], v[232:235], v[212:215], v[114:129]
	ds_read_b128 v[232:235], v209 offset:45056
	s_waitcnt lgkmcnt(4)
	v_mfma_f32_32x32x16_bf16 v[66:81], v[236:239], v[212:215], v[66:81]
	ds_read_b128 v[236:239], v209 offset:29696
	s_waitcnt lgkmcnt(4)
	v_mfma_f32_32x32x16_bf16 v[114:129], v[240:243], v[134:137], v[114:129]
	ds_read_b128 v[240:243], v209 offset:46080
	s_waitcnt lgkmcnt(4)
	v_mfma_f32_32x32x16_bf16 v[66:81], v[244:247], v[134:137], v[66:81]
	ds_read_b128 v[244:247], v209 offset:30720
	s_waitcnt lgkmcnt(4)
	v_mfma_f32_32x32x16_bf16 v[114:129], v[168:171], v[216:219], v[114:129]
	ds_read_b128 v[168:171], v209 offset:47104
	s_waitcnt lgkmcnt(4)
	v_mfma_f32_32x32x16_bf16 v[66:81], v[232:235], v[216:219], v[66:81]
	ds_read_b128 v[232:235], v209 offset:31744
	s_waitcnt lgkmcnt(4)
	v_mfma_f32_32x32x16_bf16 v[114:129], v[236:239], v[220:223], v[114:129]
	ds_read_b128 v[236:239], v209 offset:48128
	s_and_saveexec_b64 s[8:9], s[0:1]
	v_mov_b32_e32 v255, s34
	ds_write_b32 v163, v255 offset:13324
	s_or_b64 exec, exec, s[8:9]
	s_waitcnt lgkmcnt(5)
	v_mfma_f32_32x32x16_bf16 v[66:81], v[240:243], v[220:223], v[66:81]
	s_waitcnt lgkmcnt(4)
	v_mfma_f32_32x32x16_bf16 v[114:129], v[244:247], v[224:227], v[114:129]
	s_waitcnt lgkmcnt(3)
	v_mfma_f32_32x32x16_bf16 v[66:81], v[168:171], v[224:227], v[66:81]
	s_waitcnt lgkmcnt(2)
	v_mfma_f32_32x32x16_bf16 v[114:129], v[232:235], v[228:231], v[114:129]
	s_waitcnt lgkmcnt(1)
	v_mfma_f32_32x32x16_bf16 v[66:81], v[236:239], v[228:231], v[66:81]
	s_nop 7
	s_nop 7
	v_add_u32_e32 v130, v195, v140
	v_add_u32_e32 v131, 0x2000, v130
	v_cvt_pk_bf16_f32 v236, v98, v99
	v_cvt_pk_bf16_f32 v237, v100, v101
	v_cvt_pk_bf16_f32 v238, v102, v103
	v_cvt_pk_bf16_f32 v239, v104, v105
	ds_write2_b64 v131, v[236:237], v[238:239] offset0:64 offset1:66
	v_cvt_pk_bf16_f32 v240, v106, v107
	v_cvt_pk_bf16_f32 v241, v108, v109
	v_cvt_pk_bf16_f32 v242, v110, v111
	v_cvt_pk_bf16_f32 v243, v112, v113
	ds_write2_b64 v131, v[240:241], v[242:243] offset0:68 offset1:70
	v_cvt_pk_bf16_f32 v236, v114, v115
	v_cvt_pk_bf16_f32 v237, v116, v117
	v_cvt_pk_bf16_f32 v238, v118, v119
	v_cvt_pk_bf16_f32 v239, v120, v121
	ds_write2_b64 v131, v[236:237], v[238:239] offset0:72 offset1:74
	v_cvt_pk_bf16_f32 v240, v122, v123
	v_cvt_pk_bf16_f32 v241, v124, v125
	v_cvt_pk_bf16_f32 v242, v126, v127
	v_cvt_pk_bf16_f32 v243, v128, v129
	ds_write2_b64 v131, v[240:241], v[242:243] offset0:76 offset1:78
	s_waitcnt lgkmcnt(0)
	s_and_saveexec_b64 s[8:9], s[0:1]
	s_or_b64 exec, exec, s[8:9]
	ds_read_b32 v98, v163 offset:13320
	s_waitcnt lgkmcnt(0)
	v_cmp_lt_u32_e32 vcc, s7, v98
	s_cbranch_vccnz .LBB0_1515
	s_mov_b32 s4, 1
	s_branch .LBB0_1507

; #define LAS __attribute__((address_space(3)))
; __device__ __forceinline__ f32x16 mma32(bf16x8 a, bf16x8 b, f32x16 c) { return __builtin_amdgcn_mfma_f32_32x32x16_bf16(a, b, c, 0, 0, 0); }
; __device__ __forceinline__ int acc_row(int reg, int hh) { return (reg & 3) + 8 * (reg >> 2) + 4 * hh; }
; __device__ __forceinline__ void gla_scan_task(const P& p, int l, int s, int h, int sl, LAS unsigned char* ldsw, int lane) {
;     ...
;         for (int ti = 0; ti < 2; ++ti) {
;             f32x16 o = zero16();
; #pragma unroll
;             for (int ks = 0; ks < 8; ++ks) { const bf16x8 b = *(const LAS bf16x8*)(ST + r * 136 + 16 * ks + 8 * hh); o = mma32(FRAG16(bufA, 4 + ti * 8 + ks, lane), b, o); }
; #pragma unroll
;             for (int ks = 0; ks < 4; ++ks) o = mma32(FRAG16(bufA, 20 + ti * 4 + ks, lane), vb[ks], o);
; #pragma unroll
;             for (int reg = 0; reg < 16; ++reg) p.OBRAW[(size_t)(r0 + 32 * ti + acc_row(reg, hh)) * 1024 + h * 256 + 32 * sl + r] = o[reg];
.LBB0_1532:
.LBB0_1543:
	s_waitcnt lgkmcnt(0)
	v_add_u32_e32 v172, v194, v148
	v_lshl_add_u32 v132, s34, 6, v134
	s_add_i32 s7, s34, 1
	v_ashrrev_i32_e32 v133, 31, v132
	v_lshlrev_b64 v[136:137], 12, v[132:133]
	v_lshl_add_u64 v[136:137], v[130:131], 0, v[136:137]
	ds_read_b128 v[94:97], v209 offset:16384
	ds_read_b128 v[90:93], v209 offset:17408
	ds_read_b128 v[86:89], v209 offset:18432
	ds_read_b128 v[82:85], v209 offset:19456
	ds_read_b128 v[122:125], v172
	ds_read_b128 v[236:239], v209 offset:20480
	ds_read_b128 v[118:121], v172 offset:32
	ds_read_b128 v[240:243], v209 offset:21504
	ds_read_b128 v[126:129], v172 offset:64
	ds_read_b128 v[244:247], v209 offset:22528
	ds_read_b128 v[114:117], v172 offset:96
	ds_read_b128 v[168:171], v209 offset:23552
	ds_read_b128 v[110:113], v172 offset:128
	ds_read_b128 v[212:215], v209 offset:24576
	s_waitcnt lgkmcnt(8)
	v_mfma_f32_32x32x16_bf16 v[66:81], v[236:239], v[122:125], 0
	ds_read_b128 v[106:109], v172 offset:160
	ds_read_b128 v[216:219], v209 offset:25600
	ds_read_b128 v[102:105], v172 offset:192
	ds_read_b128 v[220:223], v209 offset:26624
	s_waitcnt lgkmcnt(10)
	v_mfma_f32_32x32x16_bf16 v[66:81], v[240:243], v[118:121], v[66:81]
	ds_read_b128 v[98:101], v172 offset:224
	ds_read_b128 v[224:227], v209 offset:27648
	s_waitcnt lgkmcnt(10)
	v_mfma_f32_32x32x16_bf16 v[66:81], v[244:247], v[126:129], v[66:81]
	ds_read_b128 v[228:231], v209 offset:36864
	s_waitcnt lgkmcnt(9)
	v_mfma_f32_32x32x16_bf16 v[66:81], v[168:171], v[114:117], v[66:81]
	ds_read_b128 v[232:235], v209 offset:37888
	s_waitcnt lgkmcnt(8)
	v_mfma_f32_32x32x16_bf16 v[66:81], v[212:215], v[110:113], v[66:81]
	ds_read_b128 v[236:239], v209 offset:38912
	s_waitcnt lgkmcnt(7)
	v_mfma_f32_32x32x16_bf16 v[66:81], v[216:219], v[106:109], v[66:81]
	ds_read_b128 v[240:243], v209 offset:39936
	s_and_saveexec_b64 s[8:9], s[0:1]
	v_mov_b32_e32 v255, s7
	ds_write_b32 v163, v255 offset:13336
	s_or_b64 exec, exec, s[8:9]
	s_waitcnt lgkmcnt(7)
	v_mfma_f32_32x32x16_bf16 v[66:81], v[220:223], v[102:105], v[66:81]
	s_waitcnt lgkmcnt(5)
	v_mfma_f32_32x32x16_bf16 v[66:81], v[224:227], v[98:101], v[66:81]
	s_waitcnt lgkmcnt(4)
	v_mfma_f32_32x32x16_bf16 v[66:81], v[228:231], v[94:97], v[66:81]
	s_waitcnt lgkmcnt(3)
	v_mfma_f32_32x32x16_bf16 v[66:81], v[232:235], v[90:93], v[66:81]
	s_waitcnt lgkmcnt(2)
	v_mfma_f32_32x32x16_bf16 v[66:81], v[236:239], v[86:89], v[66:81]
	s_waitcnt lgkmcnt(1)
	v_mfma_f32_32x32x16_bf16 v[66:81], v[240:243], v[82:85], v[66:81]
	s_nop 11
	v_subrev_u32_e32 v137, s100, v130
	v_lshl_add_u32 v136, v132, 12, v137
	global_store_dword v136, v66, s[100:101]
	v_add_u32_e32 v136, 0x2000, v136
	global_store_dword v136, v67, s[100:101] offset:-4096
	global_store_dword v136, v68, s[100:101]
	v_add_u32_e32 v136, 0x1000, v136
	global_store_dword v136, v69, s[100:101]
	v_add_u32_e32 v136, 0x6000, v136
	global_store_dword v136, v70, s[100:101] offset:-4096
	global_store_dword v136, v71, s[100:101]
	v_add_u32_e32 v136, 0x2000, v136
	global_store_dword v136, v72, s[100:101] offset:-4096
	global_store_dword v136, v73, s[100:101]
	v_add_u32_e32 v136, 0x6000, v136
	global_store_dword v136, v74, s[100:101] offset:-4096
	global_store_dword v136, v75, s[100:101]
	v_add_u32_e32 v136, 0x2000, v136
	global_store_dword v136, v76, s[100:101] offset:-4096
	global_store_dword v136, v77, s[100:101]
	v_add_u32_e32 v136, 0x6000, v136
	global_store_dword v136, v78, s[100:101] offset:-4096
	global_store_dword v136, v79, s[100:101]
	v_add_u32_e32 v136, 0x2000, v136
	global_store_dword v136, v80, s[100:101] offset:-4096
	global_store_dword v136, v81, s[100:101]
	s_waitcnt lgkmcnt(0)
	ds_read_b32 v255, v163 offset:13316
	s_waitcnt lgkmcnt(0)
	v_cmp_lt_u32_e32 vcc, s34, v255
	s_cbranch_vccnz .Lgp1_done
	s_mov_b32 s4, 1
	s_branch .Lgp1_1535

; #define LAS __attribute__((address_space(3)))
; __device__ __forceinline__ f32x16 mma32(bf16x8 a, bf16x8 b, f32x16 c) { return __builtin_amdgcn_mfma_f32_32x32x16_bf16(a, b, c, 0, 0, 0); }
; __device__ __forceinline__ int acc_row(int reg, int hh) { return (reg & 3) + 8 * (reg >> 2) + 4 * hh; }
; #define LDS_WAIT() asm volatile("s_waitcnt lgkmcnt(0)" ::: "memory")
; __device__ __forceinline__ void gla_scan_task(const P& p, int l, int s, int h, int sl, LAS unsigned char* ldsw, int lane) {
;     ...
;             for (int ks = 0; ks < 8; ++ks) { const bf16x8 b = *(const LAS bf16x8*)(ST + r * 136 + 16 * ks + 8 * hh); o = mma32(FRAG16(bufA, 4 + ti * 8 + ks, lane), b, o); }
; #pragma unroll
;             for (int ks = 0; ks < 4; ++ks) o = mma32(FRAG16(bufA, 20 + ti * 4 + ks, lane), vb[ks], o);
; #pragma unroll
;             for (int reg = 0; reg < 16; ++reg) p.OBRAW[(size_t)(r0 + 32 * ti + acc_row(reg, hh)) * 1024 + h * 256 + 32 * sl + r] = o[reg];
;         }
;         LDS_WAIT();
;         if (SCAN_LOADERS) { if (lane == 0) FL[3] = (unsigned)n + 1u; lds_wait_ge(FL + 2, (unsigned)n + 1u, FL + 5); }
.Lgp1_done:
	s_waitcnt lgkmcnt(0)
	ds_read_b128 v[236:239], v209 offset:28672
	ds_read_b128 v[240:243], v209 offset:29696
	ds_read_b128 v[244:247], v209 offset:30720
	ds_read_b128 v[168:171], v209 offset:31744
	ds_read_b128 v[212:215], v209 offset:32768
	ds_read_b128 v[216:219], v209 offset:33792
	s_waitcnt lgkmcnt(5)
	v_mfma_f32_32x32x16_bf16 v[66:81], v[236:239], v[122:125], 0
	ds_read_b128 v[220:223], v209 offset:34816
	s_waitcnt lgkmcnt(5)
	v_mfma_f32_32x32x16_bf16 v[66:81], v[240:243], v[118:121], v[66:81]
	ds_read_b128 v[224:227], v209 offset:35840
	s_waitcnt lgkmcnt(5)
	v_mfma_f32_32x32x16_bf16 v[66:81], v[244:247], v[126:129], v[66:81]
	ds_read_b128 v[228:231], v209 offset:40960
	s_waitcnt lgkmcnt(5)
	v_mfma_f32_32x32x16_bf16 v[66:81], v[168:171], v[114:117], v[66:81]
	ds_read_b128 v[232:235], v209 offset:41984
	s_waitcnt lgkmcnt(5)
	v_mfma_f32_32x32x16_bf16 v[66:81], v[212:215], v[110:113], v[66:81]
	ds_read_b128 v[236:239], v209 offset:43008
	s_waitcnt lgkmcnt(5)
	v_mfma_f32_32x32x16_bf16 v[66:81], v[216:219], v[106:109], v[66:81]
	ds_read_b128 v[240:243], v209 offset:44032
	s_and_saveexec_b64 s[8:9], s[0:1]
	v_mov_b32_e32 v255, s7
	ds_write_b32 v163, v255 offset:13324
	s_or_b64 exec, exec, s[8:9]
	s_waitcnt lgkmcnt(6)
	v_mfma_f32_32x32x16_bf16 v[66:81], v[220:223], v[102:105], v[66:81]
	s_waitcnt lgkmcnt(5)
	v_mfma_f32_32x32x16_bf16 v[66:81], v[224:227], v[98:101], v[66:81]
	s_waitcnt lgkmcnt(4)
	v_mfma_f32_32x32x16_bf16 v[66:81], v[228:231], v[94:97], v[66:81]
	s_waitcnt lgkmcnt(3)
	v_mfma_f32_32x32x16_bf16 v[66:81], v[232:235], v[90:93], v[66:81]
	s_waitcnt lgkmcnt(2)
	v_mfma_f32_32x32x16_bf16 v[66:81], v[236:239], v[86:89], v[66:81]
	s_waitcnt lgkmcnt(1)
	v_mfma_f32_32x32x16_bf16 v[66:81], v[240:243], v[82:85], v[66:81]
	s_nop 11
	v_subrev_u32_e32 v137, s100, v130
	v_lshl_add_u32 v136, v132, 12, v137
	v_add_u32_e32 v136, 0x21000, v136
	global_store_dword v136, v66, s[100:101] offset:-4096
	global_store_dword v136, v67, s[100:101]
	v_add_u32_e32 v136, 0x2000, v136
	global_store_dword v136, v68, s[100:101] offset:-4096
	global_store_dword v136, v69, s[100:101]
	v_add_u32_e32 v136, 0x6000, v136
	global_store_dword v136, v70, s[100:101] offset:-4096
	global_store_dword v136, v71, s[100:101]
	v_add_u32_e32 v136, 0x2000, v136
	global_store_dword v136, v72, s[100:101] offset:-4096
	global_store_dword v136, v73, s[100:101]
	v_add_u32_e32 v136, 0x6000, v136
	global_store_dword v136, v74, s[100:101] offset:-4096
	global_store_dword v136, v75, s[100:101]
	v_add_u32_e32 v136, 0x2000, v136
	global_store_dword v136, v76, s[100:101] offset:-4096
	global_store_dword v136, v77, s[100:101]
	v_add_u32_e32 v136, 0x6000, v136
	global_store_dword v136, v78, s[100:101] offset:-4096
	global_store_dword v136, v79, s[100:101]
	v_add_u32_e32 v136, 0x2000, v136
	global_store_dword v136, v80, s[100:101] offset:-4096
	global_store_dword v136, v81, s[100:101]
	s_waitcnt lgkmcnt(0)
	s_and_saveexec_b64 s[8:9], s[0:1]
	s_or_b64 exec, exec, s[8:9]
	ds_read_b32 v66, v163 offset:13320
	s_waitcnt lgkmcnt(0)
	v_cmp_lt_u32_e32 vcc, s34, v66
	s_cbranch_vccnz .LBB0_1556
	s_mov_b32 s4, 1
	s_branch .LBB0_1548
